# group-local barriers (32 workgroups with equal blockIdx%8) instead of the grid barrier at the 19 GEMM-to-GEMM phase transitions whose data stays inside the group
# speedup vs baseline: 1.0026x; 1.0026x over previous
.LBB0_1119:
	v_readlane_b32 s0, v250, 0
	v_readlane_b32 s1, v250, 1
	v_readlane_b32 s4, v250, 4
	s_cmp_lg_u32 s38, s4
	s_mov_b64 s[0:1], -1
	v_readlane_b32 s2, v250, 2
	v_readlane_b32 s3, v250, 3
	v_readlane_b32 s5, v250, 5
	v_readlane_b32 s6, v250, 6
	v_readlane_b32 s7, v250, 7
	s_cbranch_scc0 .LBB0_1173
	s_sub_u32 s98, s38, 2
	s_cmp_gt_u32 s98, 46
	s_cbranch_scc1 .Llb_global
	s_mul_i32 s99, s98, 0xaaab
	s_lshr_b32 s99, s99, 19
	s_mul_i32 s99, s99, 12
	s_sub_u32 s98, s98, s99
	s_lshr_b32 s98, 0xd81, s98
	s_and_b32 s98, s98, 1
	s_cmp_eq_u32 s98, 1
	s_cbranch_scc1 .Llb_entry
.Llb_global:
	s_waitcnt vmcnt(0)
	s_waitcnt vmcnt(0) lgkmcnt(0)
	s_barrier
	s_mov_b64 s[0:1], exec
	v_readlane_b32 s2, v250, 10
	v_readlane_b32 s3, v250, 11
	s_and_b64 s[2:3], s[0:1], s[2:3]
	s_mov_b64 exec, s[2:3]
	s_cbranch_execz .LBB0_1172
	v_readlane_b32 s2, v253, 3
	s_waitcnt vmcnt(0) expcnt(0) lgkmcnt(0)
	s_nop 0
	v_mov_b32_e32 v1, s2
	ds_read_b32 v3, v1
	v_readlane_b32 s2, v253, 4
	s_waitcnt lgkmcnt(0)
	v_cmp_ne_u32_e32 vcc, 0, v3
	v_mov_b32_e32 v1, s2
	ds_read_b32 v2, v1
	s_cbranch_vccnz .LBB0_1136
	s_mov_b32 s8, 1
	s_branch .LBB0_1124

.Llb_entry:
	s_waitcnt vmcnt(0) lgkmcnt(0)
	s_barrier
	s_mov_b64 s[0:1], exec
	v_readlane_b32 s2, v250, 10
	v_readlane_b32 s3, v250, 11
	s_and_b64 s[2:3], s[0:1], s[2:3]
	s_mov_b64 exec, s[2:3]
	s_cbranch_execz .Llb_done
	v_readlane_b32 s4, v252, 10
	v_readlane_b32 s5, v252, 11
	v_readlane_b32 s6, v253, 39
	s_and_b32 s6, s6, 7
	s_lshl_b32 s6, s6, 8
	s_add_u32 s4, s4, s6
	s_addc_u32 s5, s5, 0
	s_add_u32 s4, s4, 0x100
	s_addc_u32 s5, s5, 0
	v_mov_b32_e32 v2, 1
	s_nop 4
	global_atomic_add v2, v0, v2, s[4:5] sc0
	s_waitcnt vmcnt(0)
	v_and_b32_e32 v3, 31, v2
	v_lshrrev_b32_e32 v2, 5, v2
	v_cmp_eq_u32_e32 vcc, 31, v3
	s_nop 1
	s_cbranch_vccz .Llb_wait
	buffer_wbl2 sc1
	s_waitcnt vmcnt(0) lgkmcnt(0)
	v_mov_b32_e32 v1, 1
	global_atomic_add v0, v1, s[4:5] offset:128
	s_waitcnt vmcnt(0)
	s_branch .Llb_acq
.Llb_wait:
	s_sleep 1
	global_load_dword v3, v0, s[4:5] offset:128 sc1
	s_waitcnt vmcnt(0)
	v_cmp_eq_u32_e32 vcc, v3, v2
	s_nop 1
	s_cbranch_vccnz .Llb_wait
.Llb_acq:
	buffer_inv sc1
	s_waitcnt vmcnt(0)
.Llb_done:
	s_mov_b64 exec, s[0:1]
	s_mov_b64 s[0:1], 0
	s_waitcnt vmcnt(0) lgkmcnt(0)
	s_barrier
	s_branch .LBB0_1173
